# attention micro-diet: first-tile rescale skipped, m0 wait states filled by address adds, dead skip test removed
# baseline (speedup 1.0000x reference)
.LBB0_884:
	s_add_u32 m0, s74, 0x6000
	s_add_u32 s72, s8, s0
	s_addc_u32 s73, s9, s1
	global_load_lds_dwordx4 v164, s[72:73]
	s_add_u32 m0, s74, 0x8000
	s_nop 0
	global_load_lds_dwordx4 v170, s[72:73]
	s_add_u32 m0, s74, 0xa000
	s_nop 0
	global_load_lds_dwordx4 v168, s[72:73]
	ds_read_b128 v[146:149], v198
	ds_read_b128 v[150:153], v198 offset:8192
	ds_read_b128 v[246:249], v171
	ds_read_b128 v[250:253], v171 offset:8192
	ds_read_b128 v[180:183], v174
	ds_read_b128 v[184:187], v174 offset:8192
	s_waitcnt lgkmcnt(4)
	v_mfma_f32_32x32x16_bf16 v[82:97], v[146:149], v[98:101], v[210:225]
	v_mfma_f32_32x32x16_bf16 v[66:81], v[150:153], v[98:101], v[210:225]
	ds_read_b128 v[146:149], v175
	ds_read_b128 v[150:153], v175 offset:8192
	s_waitcnt lgkmcnt(4)
	v_mfma_f32_32x32x16_bf16 v[82:97], v[246:249], v[102:105], v[82:97]
	v_mfma_f32_32x32x16_bf16 v[66:81], v[250:253], v[102:105], v[66:81]
	ds_read_b128 v[246:249], v176
	ds_read_b128 v[250:253], v176 offset:8192
	s_waitcnt lgkmcnt(4)
	v_mfma_f32_32x32x16_bf16 v[82:97], v[180:183], v[106:109], v[82:97]
	v_mfma_f32_32x32x16_bf16 v[66:81], v[184:187], v[106:109], v[66:81]
	ds_read_b128 v[180:183], v177
	ds_read_b128 v[184:187], v177 offset:8192
	s_waitcnt lgkmcnt(4)
	v_mfma_f32_32x32x16_bf16 v[82:97], v[146:149], v[110:113], v[82:97]
	v_mfma_f32_32x32x16_bf16 v[66:81], v[150:153], v[110:113], v[66:81]
	ds_read_b128 v[146:149], v178
	ds_read_b128 v[150:153], v178 offset:8192
	s_waitcnt lgkmcnt(4)
	v_mfma_f32_32x32x16_bf16 v[82:97], v[246:249], v[122:125], v[82:97]
	v_mfma_f32_32x32x16_bf16 v[66:81], v[250:253], v[122:125], v[66:81]
	ds_read_b128 v[246:249], v179
	ds_read_b128 v[250:253], v179 offset:8192
	s_waitcnt lgkmcnt(4)
	v_mfma_f32_32x32x16_bf16 v[82:97], v[180:183], v[114:117], v[82:97]
	v_mfma_f32_32x32x16_bf16 v[66:81], v[184:187], v[114:117], v[66:81]
	ds_read_b128 v[180:183], v199
	ds_read_b128 v[184:187], v199 offset:4096
	s_waitcnt lgkmcnt(4)
	v_mfma_f32_32x32x16_bf16 v[82:97], v[146:149], v[118:121], v[82:97]
	v_mfma_f32_32x32x16_bf16 v[66:81], v[150:153], v[118:121], v[66:81]
	ds_read_b128 v[146:149], v202
	ds_read_b128 v[150:153], v202 offset:4096
	s_waitcnt lgkmcnt(4)
	v_mfma_f32_32x32x16_bf16 v[82:97], v[246:249], v[126:129], v[82:97]
	v_mfma_f32_32x32x16_bf16 v[66:81], v[250:253], v[126:129], v[66:81]
	ds_read_b128 v[246:249], v207
	ds_read_b128 v[250:253], v207 offset:4096
	s_waitcnt lgkmcnt(4)
	v_mfma_f32_32x32x16_bf16 v[82:97], v[180:183], v[130:133], v[82:97]
	v_mfma_f32_32x32x16_bf16 v[66:81], v[184:187], v[130:133], v[66:81]
	ds_read_b128 v[180:183], v208
	ds_read_b128 v[184:187], v208 offset:4096
	s_waitcnt lgkmcnt(4)
	v_mfma_f32_32x32x16_bf16 v[82:97], v[146:149], v[134:137], v[82:97]
	v_mfma_f32_32x32x16_bf16 v[66:81], v[150:153], v[134:137], v[66:81]
	s_waitcnt lgkmcnt(2)
	v_mfma_f32_32x32x16_bf16 v[82:97], v[246:249], v[138:141], v[82:97]
	v_mfma_f32_32x32x16_bf16 v[66:81], v[250:253], v[138:141], v[66:81]
	s_waitcnt lgkmcnt(0)
	v_mfma_f32_32x32x16_bf16 v[66:81], v[184:187], v[142:145], v[66:81]
	v_mfma_f32_32x32x16_bf16 v[82:97], v[180:183], v[142:145], v[82:97]
	ds_read_b64_tr_b16 v[158:159], v188 offset:0
	ds_read_b64_tr_b16 v[160:161], v189 offset:0
	ds_read_b64_tr_b16 v[154:155], v192 offset:0
	ds_read_b64_tr_b16 v[156:157], v193 offset:0
	ds_read_b64_tr_b16 v[150:151], v194 offset:0
	ds_read_b64_tr_b16 v[152:153], v195 offset:0
	ds_read_b64_tr_b16 v[146:147], v196 offset:0
	ds_read_b64_tr_b16 v[148:149], v197 offset:0
	s_nop 2
	v_max3_f32 v1, v66, v67, v68
	v_max3_f32 v180, v69, v70, v71
	v_max3_f32 v1, v1, v72, v73
	v_max3_f32 v180, v180, v74, v75
	v_max3_f32 v1, v1, v76, v77
	v_max3_f32 v180, v180, v78, v79
	v_max3_f32 v1, v1, v80, v81
	v_max3_f32 v181, v82, v83, v84
	v_max3_f32 v182, v85, v86, v87
	v_max3_f32 v181, v181, v88, v89
	v_max3_f32 v182, v182, v90, v91
	v_max3_f32 v181, v181, v92, v93
	v_max3_f32 v182, v182, v94, v95
	v_max3_f32 v181, v181, v96, v97
	v_max3_f32 v1, v1, v180, v181
	v_max_f32_e32 v1, v1, v182
	s_cmp_eq_u32 s57, 0
	s_cbranch_scc1 .Latt_rare0
	v_cmp_lt_f32_e32 vcc, 0x41000000, v1
	s_cbranch_vccz .Latt_common0
.Latt_rare0:
	v_mov_b32_e32 v180, v1
	s_nop 1
	v_permlane32_swap_b32_e32 v1, v180
	v_max_f32_e32 v1, v1, v180
	s_cmp_eq_u32 s57, 0
	s_cselect_b32 s71, 0xf149f2ca, 0
	v_max_f32_e64 v243, v1, s71
	v_max_f32_e32 v242, 0, v1
	v_exp_f32_e64 v242, -v242
	v_sub_f32_e32 v210, v210, v243
	v_sub_f32_e32 v211, v211, v243
	v_sub_f32_e32 v212, v212, v243
	v_sub_f32_e32 v213, v213, v243
	v_sub_f32_e32 v214, v214, v243
	v_sub_f32_e32 v215, v215, v243
	v_sub_f32_e32 v216, v216, v243
	v_sub_f32_e32 v217, v217, v243
	v_sub_f32_e32 v218, v218, v243
	v_sub_f32_e32 v219, v219, v243
	v_sub_f32_e32 v220, v220, v243
	v_sub_f32_e32 v221, v221, v243
	v_sub_f32_e32 v222, v222, v243
	v_sub_f32_e32 v223, v223, v243
	v_sub_f32_e32 v224, v224, v243
	v_sub_f32_e32 v225, v225, v243
	v_sub_f32_e32 v66, v66, v243
	v_sub_f32_e32 v67, v67, v243
	v_sub_f32_e32 v68, v68, v243
	v_sub_f32_e32 v69, v69, v243
	v_sub_f32_e32 v70, v70, v243
	v_sub_f32_e32 v71, v71, v243
	v_sub_f32_e32 v72, v72, v243
	v_sub_f32_e32 v73, v73, v243
	v_sub_f32_e32 v74, v74, v243
	v_sub_f32_e32 v75, v75, v243
	v_sub_f32_e32 v76, v76, v243
	v_sub_f32_e32 v77, v77, v243
	v_sub_f32_e32 v78, v78, v243
	v_sub_f32_e32 v79, v79, v243
	v_sub_f32_e32 v80, v80, v243
	v_sub_f32_e32 v81, v81, v243
	v_sub_f32_e32 v82, v82, v243
	v_sub_f32_e32 v83, v83, v243
	v_sub_f32_e32 v84, v84, v243
	v_sub_f32_e32 v85, v85, v243
	v_sub_f32_e32 v86, v86, v243
	v_sub_f32_e32 v87, v87, v243
	v_sub_f32_e32 v88, v88, v243
	v_sub_f32_e32 v89, v89, v243
	v_sub_f32_e32 v90, v90, v243
	v_sub_f32_e32 v91, v91, v243
	v_sub_f32_e32 v92, v92, v243
	v_sub_f32_e32 v93, v93, v243
	v_sub_f32_e32 v94, v94, v243
	v_sub_f32_e32 v95, v95, v243
	v_sub_f32_e32 v96, v96, v243
	v_sub_f32_e32 v97, v97, v243
	s_cmp_eq_u32 s57, 0
	s_cbranch_scc1 .Latt_common0
	v_mul_f32_e32 v173, v173, v242
	v_pk_mul_f32 v[64:65], v[64:65], v[242:243] op_sel_hi:[1,0]
	v_pk_mul_f32 v[62:63], v[62:63], v[242:243] op_sel_hi:[1,0]
	v_pk_mul_f32 v[60:61], v[60:61], v[242:243] op_sel_hi:[1,0]
	v_pk_mul_f32 v[58:59], v[58:59], v[242:243] op_sel_hi:[1,0]
	v_pk_mul_f32 v[56:57], v[56:57], v[242:243] op_sel_hi:[1,0]
	v_pk_mul_f32 v[54:55], v[54:55], v[242:243] op_sel_hi:[1,0]
	v_pk_mul_f32 v[52:53], v[52:53], v[242:243] op_sel_hi:[1,0]
	v_pk_mul_f32 v[50:51], v[50:51], v[242:243] op_sel_hi:[1,0]
	v_pk_mul_f32 v[48:49], v[48:49], v[242:243] op_sel_hi:[1,0]
	v_pk_mul_f32 v[46:47], v[46:47], v[242:243] op_sel_hi:[1,0]
	v_pk_mul_f32 v[44:45], v[44:45], v[242:243] op_sel_hi:[1,0]
	v_pk_mul_f32 v[42:43], v[42:43], v[242:243] op_sel_hi:[1,0]
	v_pk_mul_f32 v[40:41], v[40:41], v[242:243] op_sel_hi:[1,0]
	v_pk_mul_f32 v[38:39], v[38:39], v[242:243] op_sel_hi:[1,0]
	v_pk_mul_f32 v[36:37], v[36:37], v[242:243] op_sel_hi:[1,0]
	v_pk_mul_f32 v[34:35], v[34:35], v[242:243] op_sel_hi:[1,0]
	v_pk_mul_f32 v[32:33], v[32:33], v[242:243] op_sel_hi:[1,0]
	v_pk_mul_f32 v[30:31], v[30:31], v[242:243] op_sel_hi:[1,0]
	v_pk_mul_f32 v[28:29], v[28:29], v[242:243] op_sel_hi:[1,0]
	v_pk_mul_f32 v[26:27], v[26:27], v[242:243] op_sel_hi:[1,0]
	v_pk_mul_f32 v[24:25], v[24:25], v[242:243] op_sel_hi:[1,0]
	v_pk_mul_f32 v[22:23], v[22:23], v[242:243] op_sel_hi:[1,0]
	v_pk_mul_f32 v[20:21], v[20:21], v[242:243] op_sel_hi:[1,0]
	v_pk_mul_f32 v[18:19], v[18:19], v[242:243] op_sel_hi:[1,0]
	v_pk_mul_f32 v[16:17], v[16:17], v[242:243] op_sel_hi:[1,0]
	v_pk_mul_f32 v[14:15], v[14:15], v[242:243] op_sel_hi:[1,0]
	v_pk_mul_f32 v[12:13], v[12:13], v[242:243] op_sel_hi:[1,0]
	v_pk_mul_f32 v[10:11], v[10:11], v[242:243] op_sel_hi:[1,0]
	v_pk_mul_f32 v[8:9], v[8:9], v[242:243] op_sel_hi:[1,0]
	v_pk_mul_f32 v[6:7], v[6:7], v[242:243] op_sel_hi:[1,0]
	v_pk_mul_f32 v[4:5], v[4:5], v[242:243] op_sel_hi:[1,0]
	v_pk_mul_f32 v[2:3], v[2:3], v[242:243] op_sel_hi:[1,0]

.LBB0_888:
	s_cmp_ge_u32 s57, s56
	s_cselect_b64 s[12:13], -1, 0
	s_and_b64 vcc, exec, s[12:13]
	s_waitcnt vmcnt(0) lgkmcnt(0)
	s_barrier
	s_cbranch_vccnz .LBB0_890
	s_mov_b32 m0, s74
	s_add_u32 s72, s8, s6
	s_addc_u32 s73, s9, s7
	global_load_lds_dwordx4 v164, s[72:73]
	s_add_u32 m0, s74, 0x2000
	s_nop 0
	global_load_lds_dwordx4 v170, s[72:73]
	s_add_u32 m0, s74, 0x4000
	s_nop 0
	global_load_lds_dwordx4 v168, s[72:73]
